# MLA tile-loop head aligned to 64 bytes on v113
# baseline (speedup 1.0000x reference)
.LBB0_480:
	s_lshl_b32 s12, s52, 14
	s_add_i32 s52, s12, 0xc000
	s_add_u32 s53, s96, s26
	s_addc_u32 s54, s91, s27
	s_add_u32 s12, s53, 0x1d220080
	s_addc_u32 s13, s54, 0
	s_add_i32 s55, s52, s50
	s_add_i32 s55, s55, 0
	s_mov_b32 s56, m0
	s_mov_b32 m0, s55
	s_nop 0
	global_load_lds_dwordx4 v236, s[12:13]
	s_mov_b32 m0, s56
	s_add_u32 s12, s53, 0x1d230080
	s_addc_u32 s13, s54, 0
	s_add_i32 s52, s52, s51
	s_add_i32 s52, s52, 0
	s_mov_b32 s53, m0
	s_mov_b32 m0, s52
	s_nop 0
	global_load_lds_dwordx4 v236, s[12:13]
	s_mov_b32 m0, s53
	.p2align 6
